# row-sum adds inside the FoX / NSA-selected PV-overlap tails: packed v_pk_add_f32 split into two v_add_f32
# speedup vs baseline: 1.0036x; 1.0036x over previous
; template <int MODE> ...
;     ...
;             float ps = 0.f;
; #pragma unroll
;             for (int r = 0; r < 16; ++r) { s0[r] = ex2(s0[r]); s1[r] = ex2(s1[r]); ps += s0[r] + s1[r]; }
;             l += ps;
;         } else {
; #pragma unroll
;             for (int r = 0; r < 16; ++r) { s0[r] = ex2(s0[r]) * linv; s1[r] = ex2(s1[r]) * linv; }
;             float quad[8], last[8], recv[8];
; #pragma unroll
;             for (int a = 0; a < 4; ++a) {
;                 quad[a] = (s0[4 * a] + s0[4 * a + 1]) + (s0[4 * a + 2] + s0[4 * a + 3]); last[a] = s0[4 * a + 3];
;                 quad[4 + a] = (s1[4 * a] + s1[4 * a + 1]) + (s1[4 * a + 2] + s1[4 * a + 3]); last[4 + a] = s1[4 * a + 3];
;             }
; #pragma unroll
;             for (int i = 0; i < 8; ++i) recv[i] = half_other(last[i], hl);
; #pragma unroll
;             for (int i = 0; i < 8; ++i) {
;                 const float prev = (i > 0) ? recv[i > 0 ? i - 1 : 0] : carry;
;                 float v = quad[i] + (hl ? recv[i] : prev);
;                 v += __shfl_xor(v, 1); v += __shfl_xor(v, 2);
;                 if ((n & 3) == 0) lds_st<float>(L + score_ofs + (16 * kt + 2 * i + hl) * 4, v);
;             }
;             carry = recv[7];
;         }
;         if (MODE != MODE_CMP1) {
;             bf16x8 pf[4];
; #pragma unroll
;             for (int ks = 0; ks < 4; ++ks) {
;                 const int hb = 8 * (ks & 1); u32x4 w;
;                 if (ks >> 1) { w.x = cvt_pk(s1[hb], s1[hb + 1]); w.y = cvt_pk(s1[hb + 2], s1[hb + 3]); w.z = cvt_pk(s1[hb + 4], s1[hb + 5]); w.w = cvt_pk(s1[hb + 6], s1[hb + 7]); }
;                 else { w.x = cvt_pk(s0[hb], s0[hb + 1]); w.y = cvt_pk(s0[hb + 2], s0[hb + 3]); w.z = cvt_pk(s0[hb + 4], s0[hb + 5]); w.w = cvt_pk(s0[hb + 6], s0[hb + 7]); }
;                 pf[ks] = __builtin_bit_cast(bf16x8, w);
;             }
;             const lptr vb_ = Vt + (4 * hl + q4) * VP + 32 * blk + 8 * p4;
; #pragma unroll
;             for (int c_ = 0; c_ < 2; ++c_)
; #pragma unroll
;                 for (int ks_ = 0; ks_ < 4; ++ks_) {
;                     const s16x4 lo_ = tr16(vb_ + (16 * ks_) * VP + 64 * c_), hi_ = tr16(vb_ + (16 * ks_ + 8) * VP + 64 * c_);
;                     const bf16x8 vf_ = {lo_[0], lo_[1], lo_[2], lo_[3], hi_[0], hi_[1], hi_[2], hi_[3]};
;                     o[c_] = mfma32(vf_, pf[ks_], o[c_]);
;                 }
.LBB0_182:
	s_waitcnt lgkmcnt(0)
	v_exp_f32_e32 v80, v80
	v_exp_f32_e32 v81, v81
	v_exp_f32_e32 v82, v82
	v_exp_f32_e32 v83, v83
	v_exp_f32_e32 v84, v84
	v_exp_f32_e32 v85, v85
	v_exp_f32_e32 v86, v86
	v_exp_f32_e32 v87, v87
	v_cvt_pk_bf16_f32 v170, v80, v81
	v_cvt_pk_bf16_f32 v171, v82, v83
	v_add_f32_e32 v186, v80, v82
	v_add_f32_e32 v187, v81, v83
	v_cvt_pk_bf16_f32 v172, v84, v85
	v_cvt_pk_bf16_f32 v173, v86, v87
	v_add_f32_e32 v188, v84, v86
	v_add_f32_e32 v189, v85, v87
	v_exp_f32_e32 v88, v88
	v_exp_f32_e32 v89, v89
	v_exp_f32_e32 v14, v14
	v_exp_f32_e32 v15, v15
	v_mfma_f32_32x32x16_bf16 v[16:31], v[206:209], v[170:173], v[16:31]
	v_exp_f32_e32 v12, v12
	v_exp_f32_e32 v13, v13
	v_exp_f32_e32 v10, v10
	v_exp_f32_e32 v11, v11
	v_mfma_f32_32x32x16_bf16 v[32:47], v[234:237], v[170:173], v[32:47]
	v_cvt_pk_bf16_f32 v174, v88, v89
	v_add_f32_e32 v186, v186, v88
	v_add_f32_e32 v187, v187, v89
	v_cvt_pk_bf16_f32 v175, v14, v15
	v_add_f32_e32 v188, v188, v14
	v_add_f32_e32 v189, v189, v15
	v_cvt_pk_bf16_f32 v176, v12, v13
	v_add_f32_e32 v186, v186, v12
	v_add_f32_e32 v187, v187, v13
	v_cvt_pk_bf16_f32 v177, v10, v11
	v_add_f32_e32 v188, v188, v10
	v_add_f32_e32 v189, v189, v11
	v_exp_f32_e32 v64, v64
	v_exp_f32_e32 v65, v65
	v_exp_f32_e32 v66, v66
	v_exp_f32_e32 v67, v67
	v_mfma_f32_32x32x16_bf16 v[16:31], v[210:213], v[174:177], v[16:31]
	v_exp_f32_e32 v68, v68
	v_exp_f32_e32 v69, v69
	v_exp_f32_e32 v70, v70
	v_exp_f32_e32 v71, v71
	v_mfma_f32_32x32x16_bf16 v[32:47], v[238:241], v[174:177], v[32:47]
	v_cvt_pk_bf16_f32 v178, v64, v65
	v_add_f32_e32 v186, v186, v64
	v_add_f32_e32 v187, v187, v65
	v_cvt_pk_bf16_f32 v179, v66, v67
	v_add_f32_e32 v188, v188, v66
	v_add_f32_e32 v189, v189, v67
	v_cvt_pk_bf16_f32 v180, v68, v69
	v_add_f32_e32 v186, v186, v68
	v_add_f32_e32 v187, v187, v69
	v_cvt_pk_bf16_f32 v181, v70, v71
	v_add_f32_e32 v188, v188, v70
	v_add_f32_e32 v189, v189, v71
	v_exp_f32_e32 v72, v72
	v_exp_f32_e32 v73, v73
	v_exp_f32_e32 v74, v74
	v_exp_f32_e32 v75, v75
	v_mfma_f32_32x32x16_bf16 v[16:31], v[226:229], v[178:181], v[16:31]
	v_exp_f32_e32 v76, v76
	v_exp_f32_e32 v77, v77
	v_exp_f32_e32 v78, v78
	v_exp_f32_e32 v79, v79
	v_mfma_f32_32x32x16_bf16 v[32:47], v[242:245], v[178:181], v[32:47]
	v_cvt_pk_bf16_f32 v182, v72, v73
	v_add_f32_e32 v186, v186, v72
	v_add_f32_e32 v187, v187, v73
	v_cvt_pk_bf16_f32 v183, v74, v75
	v_add_f32_e32 v188, v188, v74
	v_add_f32_e32 v189, v189, v75
	v_cvt_pk_bf16_f32 v184, v76, v77
	v_add_f32_e32 v186, v186, v76
	v_add_f32_e32 v187, v187, v77
	v_cvt_pk_bf16_f32 v185, v78, v79
	v_add_f32_e32 v188, v188, v78
	v_add_f32_e32 v189, v189, v79
	v_add_f32_e32 v186, v186, v188
	v_add_f32_e32 v187, v187, v189
	s_nop 0
	v_add_f32_e32 v186, v186, v187
	v_mfma_f32_32x32x16_bf16 v[16:31], v[230:233], v[182:185], v[16:31]
	v_add_f32_e32 v140, v140, v186
	v_mfma_f32_32x32x16_bf16 v[32:47], v[246:249], v[182:185], v[32:47]
	s_or_b64 exec, exec, s[56:57]
	s_cmp_lt_i32 s7, 0
	s_cbranch_scc1 .LBB0_186

; template <int MODE> ...
;     ...
;             float ps = 0.f;
; #pragma unroll
;             for (int r = 0; r < 16; ++r) { s0[r] = ex2(s0[r]); s1[r] = ex2(s1[r]); ps += s0[r] + s1[r]; }
;             l += ps;
;         } else {
; #pragma unroll
;             for (int r = 0; r < 16; ++r) { s0[r] = ex2(s0[r]) * linv; s1[r] = ex2(s1[r]) * linv; }
;             float quad[8], last[8], recv[8];
; #pragma unroll
;             for (int a = 0; a < 4; ++a) {
;                 quad[a] = (s0[4 * a] + s0[4 * a + 1]) + (s0[4 * a + 2] + s0[4 * a + 3]); last[a] = s0[4 * a + 3];
;                 quad[4 + a] = (s1[4 * a] + s1[4 * a + 1]) + (s1[4 * a + 2] + s1[4 * a + 3]); last[4 + a] = s1[4 * a + 3];
;             }
; #pragma unroll
;             for (int i = 0; i < 8; ++i) recv[i] = half_other(last[i], hl);
; #pragma unroll
;             for (int i = 0; i < 8; ++i) {
;                 const float prev = (i > 0) ? recv[i > 0 ? i - 1 : 0] : carry;
;                 float v = quad[i] + (hl ? recv[i] : prev);
;                 v += __shfl_xor(v, 1); v += __shfl_xor(v, 2);
;                 if ((n & 3) == 0) lds_st<float>(L + score_ofs + (16 * kt + 2 * i + hl) * 4, v);
;             }
;             carry = recv[7];
;         }
;         if (MODE != MODE_CMP1) {
;             bf16x8 pf[4];
; #pragma unroll
;             for (int ks = 0; ks < 4; ++ks) {
;                 const int hb = 8 * (ks & 1); u32x4 w;
;                 if (ks >> 1) { w.x = cvt_pk(s1[hb], s1[hb + 1]); w.y = cvt_pk(s1[hb + 2], s1[hb + 3]); w.z = cvt_pk(s1[hb + 4], s1[hb + 5]); w.w = cvt_pk(s1[hb + 6], s1[hb + 7]); }
;                 else { w.x = cvt_pk(s0[hb], s0[hb + 1]); w.y = cvt_pk(s0[hb + 2], s0[hb + 3]); w.z = cvt_pk(s0[hb + 4], s0[hb + 5]); w.w = cvt_pk(s0[hb + 6], s0[hb + 7]); }
;                 pf[ks] = __builtin_bit_cast(bf16x8, w);
;             }
;             const lptr vb_ = Vt + (4 * hl + q4) * VP + 32 * blk + 8 * p4;
; #pragma unroll
;             for (int c_ = 0; c_ < 2; ++c_)
; #pragma unroll
;                 for (int ks_ = 0; ks_ < 4; ++ks_) {
;                     const s16x4 lo_ = tr16(vb_ + (16 * ks_) * VP + 64 * c_), hi_ = tr16(vb_ + (16 * ks_ + 8) * VP + 64 * c_);
;                     const bf16x8 vf_ = {lo_[0], lo_[1], lo_[2], lo_[3], hi_[0], hi_[1], hi_[2], hi_[3]};
;                     o[c_] = mfma32(vf_, pf[ks_], o[c_]);
;                 }
.LBB0_198:
	s_waitcnt lgkmcnt(0)
	v_exp_f32_e32 v80, v80
	v_exp_f32_e32 v81, v81
	v_exp_f32_e32 v82, v82
	v_exp_f32_e32 v83, v83
	v_exp_f32_e32 v84, v84
	v_exp_f32_e32 v85, v85
	v_exp_f32_e32 v86, v86
	v_exp_f32_e32 v87, v87
	v_cvt_pk_bf16_f32 v170, v80, v81
	v_cvt_pk_bf16_f32 v171, v82, v83
	v_add_f32_e32 v186, v80, v82
	v_add_f32_e32 v187, v81, v83
	v_cvt_pk_bf16_f32 v172, v84, v85
	v_cvt_pk_bf16_f32 v173, v86, v87
	v_add_f32_e32 v188, v84, v86
	v_add_f32_e32 v189, v85, v87
	v_exp_f32_e32 v88, v88
	v_exp_f32_e32 v89, v89
	v_exp_f32_e32 v14, v14
	v_exp_f32_e32 v15, v15
	v_mfma_f32_32x32x16_bf16 v[16:31], v[206:209], v[170:173], v[16:31]
	v_exp_f32_e32 v12, v12
	v_exp_f32_e32 v13, v13
	v_exp_f32_e32 v10, v10
	v_exp_f32_e32 v11, v11
	v_mfma_f32_32x32x16_bf16 v[32:47], v[234:237], v[170:173], v[32:47]
	v_cvt_pk_bf16_f32 v174, v88, v89
	v_add_f32_e32 v186, v186, v88
	v_add_f32_e32 v187, v187, v89
	v_cvt_pk_bf16_f32 v175, v14, v15
	v_add_f32_e32 v188, v188, v14
	v_add_f32_e32 v189, v189, v15
	v_cvt_pk_bf16_f32 v176, v12, v13
	v_add_f32_e32 v186, v186, v12
	v_add_f32_e32 v187, v187, v13
	v_cvt_pk_bf16_f32 v177, v10, v11
	v_add_f32_e32 v188, v188, v10
	v_add_f32_e32 v189, v189, v11
	v_exp_f32_e32 v64, v64
	v_exp_f32_e32 v65, v65
	v_exp_f32_e32 v66, v66
	v_exp_f32_e32 v67, v67
	v_mfma_f32_32x32x16_bf16 v[16:31], v[210:213], v[174:177], v[16:31]
	v_exp_f32_e32 v68, v68
	v_exp_f32_e32 v69, v69
	v_exp_f32_e32 v70, v70
	v_exp_f32_e32 v71, v71
	v_mfma_f32_32x32x16_bf16 v[32:47], v[238:241], v[174:177], v[32:47]
	v_cvt_pk_bf16_f32 v178, v64, v65
	v_add_f32_e32 v186, v186, v64
	v_add_f32_e32 v187, v187, v65
	v_cvt_pk_bf16_f32 v179, v66, v67
	v_add_f32_e32 v188, v188, v66
	v_add_f32_e32 v189, v189, v67
	v_cvt_pk_bf16_f32 v180, v68, v69
	v_add_f32_e32 v186, v186, v68
	v_add_f32_e32 v187, v187, v69
	v_cvt_pk_bf16_f32 v181, v70, v71
	v_add_f32_e32 v188, v188, v70
	v_add_f32_e32 v189, v189, v71
	v_exp_f32_e32 v72, v72
	v_exp_f32_e32 v73, v73
	v_exp_f32_e32 v74, v74
	v_exp_f32_e32 v75, v75
	v_mfma_f32_32x32x16_bf16 v[16:31], v[226:229], v[178:181], v[16:31]
	v_exp_f32_e32 v76, v76
	v_exp_f32_e32 v77, v77
	v_exp_f32_e32 v78, v78
	v_exp_f32_e32 v79, v79
	v_mfma_f32_32x32x16_bf16 v[32:47], v[242:245], v[178:181], v[32:47]
	v_cvt_pk_bf16_f32 v182, v72, v73
	v_add_f32_e32 v186, v186, v72
	v_add_f32_e32 v187, v187, v73
	v_cvt_pk_bf16_f32 v183, v74, v75
	v_add_f32_e32 v188, v188, v74
	v_add_f32_e32 v189, v189, v75
	v_cvt_pk_bf16_f32 v184, v76, v77
	v_add_f32_e32 v186, v186, v76
	v_add_f32_e32 v187, v187, v77
	v_cvt_pk_bf16_f32 v185, v78, v79
	v_add_f32_e32 v188, v188, v78
	v_add_f32_e32 v189, v189, v79
	v_add_f32_e32 v186, v186, v188
	v_add_f32_e32 v187, v187, v189
	s_nop 0
	v_add_f32_e32 v186, v186, v187
	v_mfma_f32_32x32x16_bf16 v[16:31], v[230:233], v[182:185], v[16:31]
	v_add_f32_e32 v140, v140, v186
	v_mfma_f32_32x32x16_bf16 v[32:47], v[246:249], v[182:185], v[32:47]
	s_or_b64 exec, exec, s[58:59]
	s_andn2_b64 vcc, exec, s[50:51]
	s_cbranch_vccnz .LBB0_171

; template <int MODE> ...
;     ...
;             float ps = 0.f;
; #pragma unroll
;             for (int r = 0; r < 16; ++r) { s0[r] = ex2(s0[r]); s1[r] = ex2(s1[r]); ps += s0[r] + s1[r]; }
;             l += ps;
;         } else {
; #pragma unroll
;             for (int r = 0; r < 16; ++r) { s0[r] = ex2(s0[r]) * linv; s1[r] = ex2(s1[r]) * linv; }
;             float quad[8], last[8], recv[8];
; #pragma unroll
;             for (int a = 0; a < 4; ++a) {
;                 quad[a] = (s0[4 * a] + s0[4 * a + 1]) + (s0[4 * a + 2] + s0[4 * a + 3]); last[a] = s0[4 * a + 3];
;                 quad[4 + a] = (s1[4 * a] + s1[4 * a + 1]) + (s1[4 * a + 2] + s1[4 * a + 3]); last[4 + a] = s1[4 * a + 3];
;             }
; #pragma unroll
;             for (int i = 0; i < 8; ++i) recv[i] = half_other(last[i], hl);
; #pragma unroll
;             for (int i = 0; i < 8; ++i) {
;                 const float prev = (i > 0) ? recv[i > 0 ? i - 1 : 0] : carry;
;                 float v = quad[i] + (hl ? recv[i] : prev);
;                 v += __shfl_xor(v, 1); v += __shfl_xor(v, 2);
;                 if ((n & 3) == 0) lds_st<float>(L + score_ofs + (16 * kt + 2 * i + hl) * 4, v);
;             }
;             carry = recv[7];
;         }
;         if (MODE != MODE_CMP1) {
;             bf16x8 pf[4];
; #pragma unroll
;             for (int ks = 0; ks < 4; ++ks) {
;                 const int hb = 8 * (ks & 1); u32x4 w;
;                 if (ks >> 1) { w.x = cvt_pk(s1[hb], s1[hb + 1]); w.y = cvt_pk(s1[hb + 2], s1[hb + 3]); w.z = cvt_pk(s1[hb + 4], s1[hb + 5]); w.w = cvt_pk(s1[hb + 6], s1[hb + 7]); }
;                 else { w.x = cvt_pk(s0[hb], s0[hb + 1]); w.y = cvt_pk(s0[hb + 2], s0[hb + 3]); w.z = cvt_pk(s0[hb + 4], s0[hb + 5]); w.w = cvt_pk(s0[hb + 6], s0[hb + 7]); }
;                 pf[ks] = __builtin_bit_cast(bf16x8, w);
;             }
;             const lptr vb_ = Vt + (4 * hl + q4) * VP + 32 * blk + 8 * p4;
; #pragma unroll
;             for (int c_ = 0; c_ < 2; ++c_)
; #pragma unroll
;                 for (int ks_ = 0; ks_ < 4; ++ks_) {
;                     const s16x4 lo_ = tr16(vb_ + (16 * ks_) * VP + 64 * c_), hi_ = tr16(vb_ + (16 * ks_ + 8) * VP + 64 * c_);
;                     const bf16x8 vf_ = {lo_[0], lo_[1], lo_[2], lo_[3], hi_[0], hi_[1], hi_[2], hi_[3]};
;                     o[c_] = mfma32(vf_, pf[ks_], o[c_]);
;                 }
.LBB0_317:
	s_waitcnt lgkmcnt(0)
	v_exp_f32_e32 v64, v64
	v_exp_f32_e32 v65, v65
	v_exp_f32_e32 v66, v66
	v_exp_f32_e32 v67, v67
	v_exp_f32_e32 v68, v68
	v_exp_f32_e32 v69, v69
	v_exp_f32_e32 v70, v70
	v_exp_f32_e32 v71, v71
	v_cvt_pk_bf16_f32 v10, v64, v65
	v_cvt_pk_bf16_f32 v11, v66, v67
	v_add_f32_e32 v14, v64, v66
	v_add_f32_e32 v15, v65, v67
	v_cvt_pk_bf16_f32 v12, v68, v69
	v_add_f32_e32 v14, v14, v68
	v_add_f32_e32 v15, v15, v69
	v_cvt_pk_bf16_f32 v13, v70, v71
	v_add_f32_e32 v14, v14, v70
	v_add_f32_e32 v15, v15, v71
	v_exp_f32_e32 v72, v72
	v_exp_f32_e32 v73, v73
	v_exp_f32_e32 v74, v74
	v_exp_f32_e32 v75, v75
	v_mfma_f32_32x32x16_bf16 v[32:47], v[196:199], v[10:13], v[32:47]
	v_exp_f32_e32 v76, v76
	v_exp_f32_e32 v77, v77
	v_exp_f32_e32 v78, v78
	v_exp_f32_e32 v79, v79
	v_mfma_f32_32x32x16_bf16 v[16:31], v[238:241], v[10:13], v[16:31]
	v_cvt_pk_bf16_f32 v64, v72, v73
	v_add_f32_e32 v14, v14, v72
	v_add_f32_e32 v15, v15, v73
	v_cvt_pk_bf16_f32 v65, v74, v75
	v_add_f32_e32 v14, v14, v74
	v_add_f32_e32 v15, v15, v75
	v_cvt_pk_bf16_f32 v66, v76, v77
	v_add_f32_e32 v14, v14, v76
	v_add_f32_e32 v15, v15, v77
	v_cvt_pk_bf16_f32 v67, v78, v79
	v_add_f32_e32 v14, v14, v78
	v_add_f32_e32 v15, v15, v79
	v_exp_f32_e32 v80, v80
	v_exp_f32_e32 v81, v81
	v_exp_f32_e32 v82, v82
	v_exp_f32_e32 v83, v83
	v_mfma_f32_32x32x16_bf16 v[32:47], v[200:203], v[64:67], v[32:47]
	v_exp_f32_e32 v84, v84
	v_exp_f32_e32 v85, v85
	v_exp_f32_e32 v86, v86
	v_exp_f32_e32 v87, v87
	v_mfma_f32_32x32x16_bf16 v[16:31], v[242:245], v[64:67], v[16:31]
	v_cvt_pk_bf16_f32 v68, v80, v81
	v_add_f32_e32 v14, v14, v80
	v_add_f32_e32 v15, v15, v81
	v_cvt_pk_bf16_f32 v69, v82, v83
	v_add_f32_e32 v14, v14, v82
	v_add_f32_e32 v15, v15, v83
	v_cvt_pk_bf16_f32 v70, v84, v85
	v_add_f32_e32 v14, v14, v84
	v_add_f32_e32 v15, v15, v85
	v_cvt_pk_bf16_f32 v71, v86, v87
	v_add_f32_e32 v14, v14, v86
	v_add_f32_e32 v15, v15, v87
	v_exp_f32_e32 v88, v88
	v_exp_f32_e32 v89, v89
	v_exp_f32_e32 v90, v90
	v_exp_f32_e32 v91, v91
	v_mfma_f32_32x32x16_bf16 v[32:47], v[204:207], v[68:71], v[32:47]
	v_exp_f32_e32 v92, v92
	v_exp_f32_e32 v93, v93
	v_exp_f32_e32 v94, v94
	v_exp_f32_e32 v95, v95
	v_mfma_f32_32x32x16_bf16 v[16:31], v[246:249], v[68:71], v[16:31]
	v_cvt_pk_bf16_f32 v72, v88, v89
	v_add_f32_e32 v14, v14, v88
	v_add_f32_e32 v15, v15, v89
	v_cvt_pk_bf16_f32 v73, v90, v91
	v_add_f32_e32 v14, v14, v90
	v_add_f32_e32 v15, v15, v91
	v_cvt_pk_bf16_f32 v74, v92, v93
	v_add_f32_e32 v14, v14, v92
	v_add_f32_e32 v15, v15, v93
	v_cvt_pk_bf16_f32 v75, v94, v95
	v_add_f32_e32 v14, v14, v94
	v_add_f32_e32 v15, v15, v95
	s_nop 0
	v_add_f32_e32 v14, v14, v15
	s_nop 0
	v_mfma_f32_32x32x16_bf16 v[32:47], v[208:211], v[72:75], v[32:47]
	v_add_f32_e32 v178, v178, v14
	v_mfma_f32_32x32x16_bf16 v[16:31], v[234:237], v[72:75], v[16:31]
